# rwkv_prep: the 14 serialised mu coefficient loads issued together (saddr form into free regs) and consumed with a vmcnt ladder
# baseline (speedup 1.0000x reference)
; DEVI float bf2f(bf16_t b) { return __uint_as_float(((unsigned)b) << 16); }
; DEVI bf16_t f2bf(float f) { return (bf16_t)cvt_pk_bf16(f, 0.f); }
; DEVI float sigmoidf_(float x) { return __builtin_amdgcn_rcpf(1.0f + __expf(-x)); }
; DEVI void rwkv_prep(const Params& p, int l, unsigned char* smem, int item) {
;     ...
;     bf16_t lx[14], lxp[14];
; #pragma unroll
;     for (int i = 0; i < 14; ++i) {
;         const int e = tid + i * NT, t = e / 448, j = e % 448, col = 1536 + j, tok = tok0 + t;
;         lx[i] = P[(size_t)tok * 2048 + col]; lxp[i] = tok > 0 ? P[(size_t)(tok - 1) * 2048 + col] : (bf16_t)0;
;     }
; #pragma unroll
;     for (int i = 0; i < 14; ++i) {
;         const int e = tid + i * NT;
;         const int t = e / 448, j = e % 448, col = 1536 + j;
;         const float x = bf2f(lx[i]);
;         const float xp = bf2f(lxp[i]);
;         const float xs = x + (xp - x) * mu[col];
;         float v;
;         if (j < 96) { const float e2 = __expf(2.0f * xs); v = 1.0f - 2.0f * __builtin_amdgcn_rcpf(e2 + 1.0f); }
;         else if (j < 192) v = xs;
;         else v = sigmoidf_(xs);
;         sX[t * 456 + j] = f2bf(v);
;     }
.LBB0_339:
	s_or_b64 exec, exec, s[0:1]
	v_lshlrev_b32_e32 v248, 2, v28
	v_add_u32_e32 v248, 0x1000, v248
	global_load_dword v234, v248, s[92:93] offset:2048
	v_lshlrev_b32_e32 v249, 2, v26
	v_add_u32_e32 v249, 0x1000, v249
	global_load_dword v235, v249, s[92:93] offset:2048
	v_lshlrev_b32_e32 v250, 2, v24
	v_add_u32_e32 v250, 0x1000, v250
	global_load_dword v236, v250, s[92:93] offset:2048
	v_lshlrev_b32_e32 v251, 2, v22
	v_add_u32_e32 v251, 0x1000, v251
	global_load_dword v237, v251, s[92:93] offset:2048
	v_lshlrev_b32_e32 v248, 2, v20
	v_add_u32_e32 v248, 0x1000, v248
	global_load_dword v238, v248, s[92:93] offset:2048
	v_lshlrev_b32_e32 v249, 2, v18
	v_add_u32_e32 v249, 0x1000, v249
	global_load_dword v239, v249, s[92:93] offset:2048
	v_lshlrev_b32_e32 v250, 2, v14
	v_add_u32_e32 v250, 0x1000, v250
	global_load_dword v240, v250, s[92:93] offset:2048
	v_lshlrev_b32_e32 v251, 2, v12
	v_add_u32_e32 v251, 0x1000, v251
	global_load_dword v241, v251, s[92:93] offset:2048
	v_lshlrev_b32_e32 v248, 2, v10
	v_add_u32_e32 v248, 0x1000, v248
	global_load_dword v242, v248, s[92:93] offset:2048
	v_lshlrev_b32_e32 v249, 2, v8
	v_add_u32_e32 v249, 0x1000, v249
	global_load_dword v243, v249, s[92:93] offset:2048
	v_lshlrev_b32_e32 v250, 2, v6
	v_add_u32_e32 v250, 0x1000, v250
	global_load_dword v244, v250, s[92:93] offset:2048
	v_lshlrev_b32_e32 v251, 2, v4
	v_add_u32_e32 v251, 0x1000, v251
	global_load_dword v245, v251, s[92:93] offset:2048
	v_lshlrev_b32_e32 v248, 2, v2
	v_add_u32_e32 v248, 0x1000, v248
	global_load_dword v246, v248, s[92:93] offset:2048
	v_lshlrev_b32_e32 v249, 2, v0
	v_add_u32_e32 v249, 0x1000, v249
	global_load_dword v247, v249, s[92:93] offset:2048
	s_waitcnt vmcnt(14)
	v_lshlrev_b32_e32 v58, 16, v220
	v_lshlrev_b32_e32 v55, 16, v221
	v_lshlrev_b32_e32 v54, 16, v222
	v_lshlrev_b32_e32 v51, 16, v223
	v_lshlrev_b32_e32 v50, 16, v224
	v_lshlrev_b32_e32 v47, 16, v225
	v_lshlrev_b32_e32 v46, 16, v226
	v_lshlrev_b32_e32 v43, 16, v227
	v_lshlrev_b32_e32 v42, 16, v228
	v_lshlrev_b32_e32 v39, 16, v229
	v_lshlrev_b32_e32 v38, 16, v230
	v_lshlrev_b32_e32 v35, 16, v231
	v_lshlrev_b32_e32 v34, 16, v232
	v_lshlrev_b32_e32 v1, 16, v233
	v_ashrrev_i32_e32 v29, 31, v28
	v_lshl_add_u64 v[60:61], v[28:29], 2, s[92:93]
	v_add_co_u32_e32 v60, vcc, 0x1000, v60
	v_lshlrev_b32_e32 v29, 16, v57
	v_addc_co_u32_e32 v61, vcc, 0, v61, vcc
	v_sub_f32_e32 v57, v58, v29
	v_cmp_lt_i32_e32 vcc, s77, v28
	s_waitcnt vmcnt(13)
	v_mov_b32_e32 v30, v234
	v_fmac_f32_e32 v29, v57, v30
	s_and_saveexec_b64 s[0:1], vcc
	s_xor_b64 s[0:1], exec, s[0:1]
	s_cbranch_execz .LBB0_341
	v_mul_f32_e32 v30, 0xbfb8aa3b, v29
	v_exp_f32_e32 v30, v30
	v_cmp_gt_u32_e32 vcc, s6, v28
	v_add_f32_e32 v30, 1.0, v30
	v_rcp_f32_e32 v30, v30
	s_nop 0
	v_cndmask_b32_e32 v30, v30, v29, vcc

; DEVI float bf2f(bf16_t b) { return __uint_as_float(((unsigned)b) << 16); }
; DEVI bf16_t f2bf(float f) { return (bf16_t)cvt_pk_bf16(f, 0.f); }
; DEVI float sigmoidf_(float x) { return __builtin_amdgcn_rcpf(1.0f + __expf(-x)); }
; DEVI void rwkv_prep(const Params& p, int l, unsigned char* smem, int item) {
;     ...
;     for (int i = 0; i < 14; ++i) {
;         const int e = tid + i * NT;
;         const int t = e / 448, j = e % 448, col = 1536 + j;
;         const float x = bf2f(lx[i]);
;         const float xp = bf2f(lxp[i]);
;         const float xs = x + (xp - x) * mu[col];
;         float v;
;         if (j < 96) { const float e2 = __expf(2.0f * xs); v = 1.0f - 2.0f * __builtin_amdgcn_rcpf(e2 + 1.0f); }
;         else if (j < 192) v = xs;
;         else v = sigmoidf_(xs);
;         sX[t * 456 + j] = f2bf(v);
.LBB0_343:
	s_or_b64 exec, exec, s[0:1]
	v_mul_i32_i24_e32 v27, 0x390, v27
	v_lshlrev_b32_e32 v28, 1, v28
	v_cvt_pk_bf16_f32 v29, v30, s0
	v_add3_u32 v27, 0, v27, v28
	ds_write_b16 v27, v29
	v_ashrrev_i32_e32 v27, 31, v26
	v_lshlrev_b32_e32 v28, 16, v56
	v_lshl_add_u64 v[56:57], v[26:27], 2, s[92:93]
	v_add_co_u32_e32 v56, vcc, 0x1000, v56
	v_sub_f32_e32 v29, v55, v28
	s_nop 0
	v_addc_co_u32_e32 v57, vcc, 0, v57, vcc
	v_cmp_lt_i32_e32 vcc, s77, v26
	s_waitcnt vmcnt(12)
	v_mov_b32_e32 v27, v235
	v_fmac_f32_e32 v28, v29, v27
	s_and_saveexec_b64 s[0:1], vcc
	s_xor_b64 s[0:1], exec, s[0:1]
	s_cbranch_execz .LBB0_345
	v_mul_f32_e32 v27, 0xbfb8aa3b, v28
	v_exp_f32_e32 v27, v27
	v_cmp_gt_u32_e32 vcc, s6, v26
	v_add_f32_e32 v27, 1.0, v27
	v_rcp_f32_e32 v27, v27
	s_nop 0
	v_cndmask_b32_e32 v27, v27, v28, vcc

; DEVI float bf2f(bf16_t b) { return __uint_as_float(((unsigned)b) << 16); }
; DEVI bf16_t f2bf(float f) { return (bf16_t)cvt_pk_bf16(f, 0.f); }
; DEVI float sigmoidf_(float x) { return __builtin_amdgcn_rcpf(1.0f + __expf(-x)); }
; DEVI void rwkv_prep(const Params& p, int l, unsigned char* smem, int item) {
;     ...
;     for (int i = 0; i < 14; ++i) {
;         const int e = tid + i * NT;
;         const int t = e / 448, j = e % 448, col = 1536 + j;
;         const float x = bf2f(lx[i]);
;         const float xp = bf2f(lxp[i]);
;         const float xs = x + (xp - x) * mu[col];
;         float v;
;         if (j < 96) { const float e2 = __expf(2.0f * xs); v = 1.0f - 2.0f * __builtin_amdgcn_rcpf(e2 + 1.0f); }
;         else if (j < 192) v = xs;
;         else v = sigmoidf_(xs);
;         sX[t * 456 + j] = f2bf(v);
.LBB0_347:
	s_or_b64 exec, exec, s[0:1]
	v_mul_i32_i24_e32 v25, 0x390, v25
	v_lshlrev_b32_e32 v26, 1, v26
	v_cvt_pk_bf16_f32 v27, v27, s0
	v_add3_u32 v25, 0, v25, v26
	ds_write_b16 v25, v27
	v_ashrrev_i32_e32 v25, 31, v24
	v_lshl_add_u64 v[28:29], v[24:25], 2, s[92:93]
	v_add_co_u32_e32 v28, vcc, 0x1000, v28
	v_lshlrev_b32_e32 v26, 16, v53
	s_nop 0
	v_addc_co_u32_e32 v29, vcc, 0, v29, vcc
	v_sub_f32_e32 v27, v54, v26
	v_cmp_lt_i32_e32 vcc, s77, v24
	s_waitcnt vmcnt(11)
	v_mov_b32_e32 v25, v236
	v_fmac_f32_e32 v26, v27, v25
	s_and_saveexec_b64 s[0:1], vcc
	s_xor_b64 s[0:1], exec, s[0:1]
	s_cbranch_execz .LBB0_349
	v_mul_f32_e32 v25, 0xbfb8aa3b, v26
	v_exp_f32_e32 v25, v25
	v_cmp_gt_u32_e32 vcc, s6, v24
	v_add_f32_e32 v25, 1.0, v25
	v_rcp_f32_e32 v25, v25
	s_nop 0
	v_cndmask_b32_e32 v25, v25, v26, vcc

; DEVI float bf2f(bf16_t b) { return __uint_as_float(((unsigned)b) << 16); }
; DEVI bf16_t f2bf(float f) { return (bf16_t)cvt_pk_bf16(f, 0.f); }
; DEVI float sigmoidf_(float x) { return __builtin_amdgcn_rcpf(1.0f + __expf(-x)); }
; DEVI void rwkv_prep(const Params& p, int l, unsigned char* smem, int item) {
;     ...
;     for (int i = 0; i < 14; ++i) {
;         const int e = tid + i * NT;
;         const int t = e / 448, j = e % 448, col = 1536 + j;
;         const float x = bf2f(lx[i]);
;         const float xp = bf2f(lxp[i]);
;         const float xs = x + (xp - x) * mu[col];
;         float v;
;         if (j < 96) { const float e2 = __expf(2.0f * xs); v = 1.0f - 2.0f * __builtin_amdgcn_rcpf(e2 + 1.0f); }
;         else if (j < 192) v = xs;
;         else v = sigmoidf_(xs);
;         sX[t * 456 + j] = f2bf(v);
.LBB0_351:
	s_or_b64 exec, exec, s[0:1]
	v_mul_i32_i24_e32 v23, 0x390, v23
	v_lshlrev_b32_e32 v24, 1, v24
	v_cvt_pk_bf16_f32 v25, v25, s0
	v_add3_u32 v23, 0, v23, v24
	ds_write_b16 v23, v25
	v_ashrrev_i32_e32 v23, 31, v22
	v_lshl_add_u64 v[26:27], v[22:23], 2, s[92:93]
	v_add_co_u32_e32 v26, vcc, 0x1000, v26
	v_lshlrev_b32_e32 v24, 16, v52
	s_nop 0
	v_addc_co_u32_e32 v27, vcc, 0, v27, vcc
	v_sub_f32_e32 v25, v51, v24
	v_cmp_lt_i32_e32 vcc, s77, v22
	s_waitcnt vmcnt(10)
	v_mov_b32_e32 v23, v237
	v_fmac_f32_e32 v24, v25, v23
	s_and_saveexec_b64 s[0:1], vcc
	s_xor_b64 s[0:1], exec, s[0:1]
	s_cbranch_execz .LBB0_353
	v_mul_f32_e32 v23, 0xbfb8aa3b, v24
	v_exp_f32_e32 v23, v23
	v_cmp_gt_u32_e32 vcc, s6, v22
	v_add_f32_e32 v23, 1.0, v23
	v_rcp_f32_e32 v23, v23
	s_nop 0
	v_cndmask_b32_e32 v23, v23, v24, vcc

; DEVI float bf2f(bf16_t b) { return __uint_as_float(((unsigned)b) << 16); }
; DEVI bf16_t f2bf(float f) { return (bf16_t)cvt_pk_bf16(f, 0.f); }
; DEVI float sigmoidf_(float x) { return __builtin_amdgcn_rcpf(1.0f + __expf(-x)); }
; DEVI void rwkv_prep(const Params& p, int l, unsigned char* smem, int item) {
;     ...
;     for (int i = 0; i < 14; ++i) {
;         const int e = tid + i * NT;
;         const int t = e / 448, j = e % 448, col = 1536 + j;
;         const float x = bf2f(lx[i]);
;         const float xp = bf2f(lxp[i]);
;         const float xs = x + (xp - x) * mu[col];
;         float v;
;         if (j < 96) { const float e2 = __expf(2.0f * xs); v = 1.0f - 2.0f * __builtin_amdgcn_rcpf(e2 + 1.0f); }
;         else if (j < 192) v = xs;
;         else v = sigmoidf_(xs);
;         sX[t * 456 + j] = f2bf(v);
.LBB0_355:
	s_or_b64 exec, exec, s[0:1]
	v_mul_i32_i24_e32 v21, 0x390, v21
	v_lshlrev_b32_e32 v22, 1, v22
	v_cvt_pk_bf16_f32 v23, v23, s0
	v_add3_u32 v21, 0, v21, v22
	ds_write_b16 v21, v23
	v_ashrrev_i32_e32 v21, 31, v20
	v_lshl_add_u64 v[24:25], v[20:21], 2, s[92:93]
	v_add_co_u32_e32 v24, vcc, 0x1000, v24
	v_lshlrev_b32_e32 v22, 16, v49
	s_nop 0
	v_addc_co_u32_e32 v25, vcc, 0, v25, vcc
	v_sub_f32_e32 v23, v50, v22
	v_cmp_lt_i32_e32 vcc, s77, v20
	s_waitcnt vmcnt(9)
	v_mov_b32_e32 v21, v238
	v_fmac_f32_e32 v22, v23, v21
	s_and_saveexec_b64 s[0:1], vcc
	s_xor_b64 s[0:1], exec, s[0:1]
	s_cbranch_execz .LBB0_357
	v_mul_f32_e32 v21, 0xbfb8aa3b, v22
	v_exp_f32_e32 v21, v21
	v_cmp_gt_u32_e32 vcc, s6, v20
	v_add_f32_e32 v21, 1.0, v21
	v_rcp_f32_e32 v21, v21
	s_nop 0
	v_cndmask_b32_e32 v21, v21, v22, vcc

; DEVI float bf2f(bf16_t b) { return __uint_as_float(((unsigned)b) << 16); }
; DEVI bf16_t f2bf(float f) { return (bf16_t)cvt_pk_bf16(f, 0.f); }
; DEVI float sigmoidf_(float x) { return __builtin_amdgcn_rcpf(1.0f + __expf(-x)); }
; DEVI void rwkv_prep(const Params& p, int l, unsigned char* smem, int item) {
;     ...
;     for (int i = 0; i < 14; ++i) {
;         const int e = tid + i * NT;
;         const int t = e / 448, j = e % 448, col = 1536 + j;
;         const float x = bf2f(lx[i]);
;         const float xp = bf2f(lxp[i]);
;         const float xs = x + (xp - x) * mu[col];
;         float v;
;         if (j < 96) { const float e2 = __expf(2.0f * xs); v = 1.0f - 2.0f * __builtin_amdgcn_rcpf(e2 + 1.0f); }
;         else if (j < 192) v = xs;
;         else v = sigmoidf_(xs);
;         sX[t * 456 + j] = f2bf(v);
.LBB0_359:
	s_or_b64 exec, exec, s[0:1]
	v_mul_i32_i24_e32 v19, 0x390, v19
	v_lshlrev_b32_e32 v20, 1, v20
	v_cvt_pk_bf16_f32 v21, v21, s0
	v_add3_u32 v19, 0, v19, v20
	ds_write_b16 v19, v21
	v_ashrrev_i32_e32 v19, 31, v18
	v_lshl_add_u64 v[22:23], v[18:19], 2, s[92:93]
	v_add_co_u32_e32 v22, vcc, 0x1000, v22
	v_lshlrev_b32_e32 v20, 16, v48
	s_nop 0
	v_addc_co_u32_e32 v23, vcc, 0, v23, vcc
	v_sub_f32_e32 v21, v47, v20
	v_cmp_lt_i32_e32 vcc, s77, v18
	s_waitcnt vmcnt(8)
	v_mov_b32_e32 v19, v239
	v_fmac_f32_e32 v20, v21, v19
	s_and_saveexec_b64 s[0:1], vcc
	s_xor_b64 s[0:1], exec, s[0:1]
	s_cbranch_execz .LBB0_361
	v_mul_f32_e32 v19, 0xbfb8aa3b, v20
	v_exp_f32_e32 v19, v19
	v_cmp_gt_u32_e32 vcc, s6, v18
	v_add_f32_e32 v19, 1.0, v19
	v_rcp_f32_e32 v19, v19
	s_nop 0
	v_cndmask_b32_e32 v19, v19, v20, vcc

; DEVI float bf2f(bf16_t b) { return __uint_as_float(((unsigned)b) << 16); }
; DEVI bf16_t f2bf(float f) { return (bf16_t)cvt_pk_bf16(f, 0.f); }
; DEVI float sigmoidf_(float x) { return __builtin_amdgcn_rcpf(1.0f + __expf(-x)); }
; DEVI void rwkv_prep(const Params& p, int l, unsigned char* smem, int item) {
;     ...
;     for (int i = 0; i < 14; ++i) {
;         const int e = tid + i * NT;
;         const int t = e / 448, j = e % 448, col = 1536 + j;
;         const float x = bf2f(lx[i]);
;         const float xp = bf2f(lxp[i]);
;         const float xs = x + (xp - x) * mu[col];
;         float v;
;         if (j < 96) { const float e2 = __expf(2.0f * xs); v = 1.0f - 2.0f * __builtin_amdgcn_rcpf(e2 + 1.0f); }
;         else if (j < 192) v = xs;
;         else v = sigmoidf_(xs);
;         sX[t * 456 + j] = f2bf(v);
.LBB0_363:
	s_or_b64 exec, exec, s[0:1]
	v_mul_i32_i24_e32 v15, 0x390, v15
	v_lshlrev_b32_e32 v18, 1, v18
	v_cvt_pk_bf16_f32 v19, v19, s0
	v_add3_u32 v15, 0, v15, v18
	ds_write_b16 v15, v19
	v_ashrrev_i32_e32 v15, 31, v14
	v_lshl_add_u64 v[20:21], v[14:15], 2, s[92:93]
	v_add_co_u32_e32 v20, vcc, 0x1000, v20
	v_lshlrev_b32_e32 v18, 16, v45
	s_nop 0
	v_addc_co_u32_e32 v21, vcc, 0, v21, vcc
	v_sub_f32_e32 v19, v46, v18
	v_cmp_lt_i32_e32 vcc, s77, v14
	s_waitcnt vmcnt(7)
	v_mov_b32_e32 v15, v240
	v_fmac_f32_e32 v18, v19, v15
	s_and_saveexec_b64 s[0:1], vcc
	s_xor_b64 s[0:1], exec, s[0:1]
	s_cbranch_execz .LBB0_365
	v_mul_f32_e32 v15, 0xbfb8aa3b, v18
	v_exp_f32_e32 v15, v15
	v_cmp_gt_u32_e32 vcc, s6, v14
	v_add_f32_e32 v15, 1.0, v15
	v_rcp_f32_e32 v15, v15
	s_nop 0
	v_cndmask_b32_e32 v15, v15, v18, vcc

; DEVI float bf2f(bf16_t b) { return __uint_as_float(((unsigned)b) << 16); }
; DEVI bf16_t f2bf(float f) { return (bf16_t)cvt_pk_bf16(f, 0.f); }
; DEVI float sigmoidf_(float x) { return __builtin_amdgcn_rcpf(1.0f + __expf(-x)); }
; DEVI void rwkv_prep(const Params& p, int l, unsigned char* smem, int item) {
;     ...
;     for (int i = 0; i < 14; ++i) {
;         const int e = tid + i * NT;
;         const int t = e / 448, j = e % 448, col = 1536 + j;
;         const float x = bf2f(lx[i]);
;         const float xp = bf2f(lxp[i]);
;         const float xs = x + (xp - x) * mu[col];
;         float v;
;         if (j < 96) { const float e2 = __expf(2.0f * xs); v = 1.0f - 2.0f * __builtin_amdgcn_rcpf(e2 + 1.0f); }
;         else if (j < 192) v = xs;
;         else v = sigmoidf_(xs);
;         sX[t * 456 + j] = f2bf(v);
.LBB0_367:
	s_or_b64 exec, exec, s[0:1]
	v_mul_i32_i24_e32 v13, 0x390, v13
	v_lshlrev_b32_e32 v14, 1, v14
	v_cvt_pk_bf16_f32 v15, v15, s0
	v_add3_u32 v13, 0, v13, v14
	ds_write_b16 v13, v15
	v_ashrrev_i32_e32 v13, 31, v12
	v_lshl_add_u64 v[18:19], v[12:13], 2, s[92:93]
	v_add_co_u32_e32 v18, vcc, 0x1000, v18
	v_lshlrev_b32_e32 v14, 16, v44
	s_nop 0
	v_addc_co_u32_e32 v19, vcc, 0, v19, vcc
	v_sub_f32_e32 v15, v43, v14
	v_cmp_lt_i32_e32 vcc, s77, v12
	s_waitcnt vmcnt(6)
	v_mov_b32_e32 v13, v241
	v_fmac_f32_e32 v14, v15, v13
	s_and_saveexec_b64 s[0:1], vcc
	s_xor_b64 s[0:1], exec, s[0:1]
	s_cbranch_execz .LBB0_369
	v_mul_f32_e32 v13, 0xbfb8aa3b, v14
	v_exp_f32_e32 v13, v13
	v_cmp_gt_u32_e32 vcc, s6, v12
	v_add_f32_e32 v13, 1.0, v13
	v_rcp_f32_e32 v13, v13
	s_nop 0
	v_cndmask_b32_e32 v13, v13, v14, vcc

; DEVI float bf2f(bf16_t b) { return __uint_as_float(((unsigned)b) << 16); }
; DEVI bf16_t f2bf(float f) { return (bf16_t)cvt_pk_bf16(f, 0.f); }
; DEVI float sigmoidf_(float x) { return __builtin_amdgcn_rcpf(1.0f + __expf(-x)); }
; DEVI void rwkv_prep(const Params& p, int l, unsigned char* smem, int item) {
;     ...
;     for (int i = 0; i < 14; ++i) {
;         const int e = tid + i * NT;
;         const int t = e / 448, j = e % 448, col = 1536 + j;
;         const float x = bf2f(lx[i]);
;         const float xp = bf2f(lxp[i]);
;         const float xs = x + (xp - x) * mu[col];
;         float v;
;         if (j < 96) { const float e2 = __expf(2.0f * xs); v = 1.0f - 2.0f * __builtin_amdgcn_rcpf(e2 + 1.0f); }
;         else if (j < 192) v = xs;
;         else v = sigmoidf_(xs);
;         sX[t * 456 + j] = f2bf(v);
.LBB0_371:
	s_or_b64 exec, exec, s[0:1]
	v_mul_i32_i24_e32 v11, 0x390, v11
	v_lshlrev_b32_e32 v12, 1, v12
	v_cvt_pk_bf16_f32 v13, v13, s0
	v_add3_u32 v11, 0, v11, v12
	ds_write_b16 v11, v13
	v_ashrrev_i32_e32 v11, 31, v10
	v_lshl_add_u64 v[14:15], v[10:11], 2, s[92:93]
	v_add_co_u32_e32 v14, vcc, 0x1000, v14
	v_lshlrev_b32_e32 v12, 16, v41
	s_nop 0
	v_addc_co_u32_e32 v15, vcc, 0, v15, vcc
	v_sub_f32_e32 v13, v42, v12
	v_cmp_lt_i32_e32 vcc, s77, v10
	s_waitcnt vmcnt(5)
	v_mov_b32_e32 v11, v242
	v_fmac_f32_e32 v12, v13, v11
	s_and_saveexec_b64 s[0:1], vcc
	s_xor_b64 s[0:1], exec, s[0:1]
	s_cbranch_execz .LBB0_373
	v_mul_f32_e32 v11, 0xbfb8aa3b, v12
	v_exp_f32_e32 v11, v11
	v_cmp_gt_u32_e32 vcc, s6, v10
	v_add_f32_e32 v11, 1.0, v11
	v_rcp_f32_e32 v11, v11
	s_nop 0
	v_cndmask_b32_e32 v11, v11, v12, vcc

; DEVI float bf2f(bf16_t b) { return __uint_as_float(((unsigned)b) << 16); }
; DEVI bf16_t f2bf(float f) { return (bf16_t)cvt_pk_bf16(f, 0.f); }
; DEVI float sigmoidf_(float x) { return __builtin_amdgcn_rcpf(1.0f + __expf(-x)); }
; DEVI void rwkv_prep(const Params& p, int l, unsigned char* smem, int item) {
;     ...
;     for (int i = 0; i < 14; ++i) {
;         const int e = tid + i * NT;
;         const int t = e / 448, j = e % 448, col = 1536 + j;
;         const float x = bf2f(lx[i]);
;         const float xp = bf2f(lxp[i]);
;         const float xs = x + (xp - x) * mu[col];
;         float v;
;         if (j < 96) { const float e2 = __expf(2.0f * xs); v = 1.0f - 2.0f * __builtin_amdgcn_rcpf(e2 + 1.0f); }
;         else if (j < 192) v = xs;
;         else v = sigmoidf_(xs);
;         sX[t * 456 + j] = f2bf(v);
.LBB0_375:
	s_or_b64 exec, exec, s[0:1]
	v_mul_i32_i24_e32 v9, 0x390, v9
	v_lshlrev_b32_e32 v10, 1, v10
	v_cvt_pk_bf16_f32 v11, v11, s0
	v_add3_u32 v9, 0, v9, v10
	ds_write_b16 v9, v11
	v_ashrrev_i32_e32 v9, 31, v8
	v_lshl_add_u64 v[12:13], v[8:9], 2, s[92:93]
	v_add_co_u32_e32 v12, vcc, 0x1000, v12
	v_lshlrev_b32_e32 v10, 16, v40
	s_nop 0
	v_addc_co_u32_e32 v13, vcc, 0, v13, vcc
	v_sub_f32_e32 v11, v39, v10
	v_cmp_lt_i32_e32 vcc, s77, v8
	s_waitcnt vmcnt(4)
	v_mov_b32_e32 v9, v243
	v_fmac_f32_e32 v10, v11, v9
	s_and_saveexec_b64 s[0:1], vcc
	s_xor_b64 s[0:1], exec, s[0:1]
	s_cbranch_execz .LBB0_377
	v_mul_f32_e32 v9, 0xbfb8aa3b, v10
	v_exp_f32_e32 v9, v9
	v_cmp_gt_u32_e32 vcc, s6, v8
	v_add_f32_e32 v9, 1.0, v9
	v_rcp_f32_e32 v9, v9
	s_nop 0
	v_cndmask_b32_e32 v9, v9, v10, vcc

; DEVI float bf2f(bf16_t b) { return __uint_as_float(((unsigned)b) << 16); }
; DEVI bf16_t f2bf(float f) { return (bf16_t)cvt_pk_bf16(f, 0.f); }
; DEVI float sigmoidf_(float x) { return __builtin_amdgcn_rcpf(1.0f + __expf(-x)); }
; DEVI void rwkv_prep(const Params& p, int l, unsigned char* smem, int item) {
;     ...
;     for (int i = 0; i < 14; ++i) {
;         const int e = tid + i * NT;
;         const int t = e / 448, j = e % 448, col = 1536 + j;
;         const float x = bf2f(lx[i]);
;         const float xp = bf2f(lxp[i]);
;         const float xs = x + (xp - x) * mu[col];
;         float v;
;         if (j < 96) { const float e2 = __expf(2.0f * xs); v = 1.0f - 2.0f * __builtin_amdgcn_rcpf(e2 + 1.0f); }
;         else if (j < 192) v = xs;
;         else v = sigmoidf_(xs);
;         sX[t * 456 + j] = f2bf(v);
.LBB0_379:
	s_or_b64 exec, exec, s[0:1]
	v_mul_i32_i24_e32 v7, 0x390, v7
	v_lshlrev_b32_e32 v8, 1, v8
	v_cvt_pk_bf16_f32 v9, v9, s0
	v_add3_u32 v7, 0, v7, v8
	ds_write_b16 v7, v9
	v_ashrrev_i32_e32 v7, 31, v6
	v_lshl_add_u64 v[10:11], v[6:7], 2, s[92:93]
	v_add_co_u32_e32 v10, vcc, 0x1000, v10
	v_lshlrev_b32_e32 v8, 16, v37
	s_nop 0
	v_addc_co_u32_e32 v11, vcc, 0, v11, vcc
	v_sub_f32_e32 v9, v38, v8
	v_cmp_lt_i32_e32 vcc, s77, v6
	s_waitcnt vmcnt(3)
	v_mov_b32_e32 v7, v244
	v_fmac_f32_e32 v8, v9, v7
	s_and_saveexec_b64 s[0:1], vcc
	s_xor_b64 s[0:1], exec, s[0:1]
	s_cbranch_execz .LBB0_381
	v_mul_f32_e32 v7, 0xbfb8aa3b, v8
	v_exp_f32_e32 v7, v7
	v_cmp_gt_u32_e32 vcc, s6, v6
	v_add_f32_e32 v7, 1.0, v7
	v_rcp_f32_e32 v7, v7
	s_nop 0
	v_cndmask_b32_e32 v7, v7, v8, vcc

; DEVI float bf2f(bf16_t b) { return __uint_as_float(((unsigned)b) << 16); }
; DEVI bf16_t f2bf(float f) { return (bf16_t)cvt_pk_bf16(f, 0.f); }
; DEVI float sigmoidf_(float x) { return __builtin_amdgcn_rcpf(1.0f + __expf(-x)); }
; DEVI void rwkv_prep(const Params& p, int l, unsigned char* smem, int item) {
;     ...
;     for (int i = 0; i < 14; ++i) {
;         const int e = tid + i * NT;
;         const int t = e / 448, j = e % 448, col = 1536 + j;
;         const float x = bf2f(lx[i]);
;         const float xp = bf2f(lxp[i]);
;         const float xs = x + (xp - x) * mu[col];
;         float v;
;         if (j < 96) { const float e2 = __expf(2.0f * xs); v = 1.0f - 2.0f * __builtin_amdgcn_rcpf(e2 + 1.0f); }
;         else if (j < 192) v = xs;
;         else v = sigmoidf_(xs);
;         sX[t * 456 + j] = f2bf(v);
.LBB0_383:
	s_or_b64 exec, exec, s[0:1]
	v_mul_i32_i24_e32 v5, 0x390, v5
	v_lshlrev_b32_e32 v6, 1, v6
	v_cvt_pk_bf16_f32 v7, v7, s0
	v_add3_u32 v5, 0, v5, v6
	ds_write_b16 v5, v7
	v_ashrrev_i32_e32 v5, 31, v4
	v_lshl_add_u64 v[8:9], v[4:5], 2, s[92:93]
	v_add_co_u32_e32 v8, vcc, 0x1000, v8
	v_lshlrev_b32_e32 v6, 16, v36
	s_nop 0
	v_addc_co_u32_e32 v9, vcc, 0, v9, vcc
	v_sub_f32_e32 v7, v35, v6
	v_cmp_lt_i32_e32 vcc, s77, v4
	s_waitcnt vmcnt(2)
	v_mov_b32_e32 v5, v245
	v_fmac_f32_e32 v6, v7, v5
	s_and_saveexec_b64 s[0:1], vcc
	s_xor_b64 s[0:1], exec, s[0:1]
	s_cbranch_execz .LBB0_385
	v_mul_f32_e32 v5, 0xbfb8aa3b, v6
	v_exp_f32_e32 v5, v5
	v_cmp_gt_u32_e32 vcc, s6, v4
	v_add_f32_e32 v5, 1.0, v5
	v_rcp_f32_e32 v5, v5
	s_nop 0
	v_cndmask_b32_e32 v5, v5, v6, vcc

; DEVI float bf2f(bf16_t b) { return __uint_as_float(((unsigned)b) << 16); }
; DEVI bf16_t f2bf(float f) { return (bf16_t)cvt_pk_bf16(f, 0.f); }
; DEVI float sigmoidf_(float x) { return __builtin_amdgcn_rcpf(1.0f + __expf(-x)); }
; DEVI void rwkv_prep(const Params& p, int l, unsigned char* smem, int item) {
;     ...
;     for (int i = 0; i < 14; ++i) {
;         const int e = tid + i * NT;
;         const int t = e / 448, j = e % 448, col = 1536 + j;
;         const float x = bf2f(lx[i]);
;         const float xp = bf2f(lxp[i]);
;         const float xs = x + (xp - x) * mu[col];
;         float v;
;         if (j < 96) { const float e2 = __expf(2.0f * xs); v = 1.0f - 2.0f * __builtin_amdgcn_rcpf(e2 + 1.0f); }
;         else if (j < 192) v = xs;
;         else v = sigmoidf_(xs);
;         sX[t * 456 + j] = f2bf(v);
.LBB0_387:
	s_or_b64 exec, exec, s[0:1]
	v_mul_i32_i24_e32 v3, 0x390, v3
	v_lshlrev_b32_e32 v4, 1, v4
	v_cvt_pk_bf16_f32 v5, v5, s0
	v_add3_u32 v3, 0, v3, v4
	ds_write_b16 v3, v5
	v_ashrrev_i32_e32 v3, 31, v2
	v_lshl_add_u64 v[6:7], v[2:3], 2, s[92:93]
	v_add_co_u32_e32 v6, vcc, 0x1000, v6
	v_lshlrev_b32_e32 v4, 16, v33
	s_nop 0
	v_addc_co_u32_e32 v7, vcc, 0, v7, vcc
	v_sub_f32_e32 v5, v34, v4
	v_cmp_lt_i32_e32 vcc, s77, v2
	s_waitcnt vmcnt(1)
	v_mov_b32_e32 v3, v246
	v_fmac_f32_e32 v4, v5, v3
	s_and_saveexec_b64 s[0:1], vcc
	s_xor_b64 s[0:1], exec, s[0:1]
	s_cbranch_execz .LBB0_389
	v_mul_f32_e32 v3, 0xbfb8aa3b, v4
	v_exp_f32_e32 v3, v3
	v_cmp_gt_u32_e32 vcc, s6, v2
	v_add_f32_e32 v3, 1.0, v3
	v_rcp_f32_e32 v3, v3
	s_nop 0
	v_cndmask_b32_e32 v3, v3, v4, vcc

; DEVI float bf2f(bf16_t b) { return __uint_as_float(((unsigned)b) << 16); }
; DEVI bf16_t f2bf(float f) { return (bf16_t)cvt_pk_bf16(f, 0.f); }
; DEVI float sigmoidf_(float x) { return __builtin_amdgcn_rcpf(1.0f + __expf(-x)); }
; DEVI void rwkv_prep(const Params& p, int l, unsigned char* smem, int item) {
;     ...
;     for (int i = 0; i < 14; ++i) {
;         const int e = tid + i * NT;
;         const int t = e / 448, j = e % 448, col = 1536 + j;
;         const float x = bf2f(lx[i]);
;         const float xp = bf2f(lxp[i]);
;         const float xs = x + (xp - x) * mu[col];
;         float v;
;         if (j < 96) { const float e2 = __expf(2.0f * xs); v = 1.0f - 2.0f * __builtin_amdgcn_rcpf(e2 + 1.0f); }
;         else if (j < 192) v = xs;
;         else v = sigmoidf_(xs);
;         sX[t * 456 + j] = f2bf(v);
.LBB0_391:
	s_or_b64 exec, exec, s[0:1]
	v_mul_i32_i24_e32 v4, 0x390, v32
	v_lshlrev_b32_e32 v2, 1, v2
	v_cvt_pk_bf16_f32 v3, v3, s0
	v_add3_u32 v2, 0, v4, v2
	ds_write_b16 v2, v3
	v_lshlrev_b32_e32 v2, 16, v31
	v_sub_f32_e32 v3, v1, v2
	v_ashrrev_i32_e32 v1, 31, v0
	v_lshl_add_u64 v[4:5], v[0:1], 2, s[92:93]
	v_add_co_u32_e32 v4, vcc, 0x1000, v4
	s_nop 1
	v_addc_co_u32_e32 v5, vcc, 0, v5, vcc
	v_cmp_lt_i32_e32 vcc, s77, v0
	s_waitcnt vmcnt(0)
	v_mov_b32_e32 v1, v247
	v_fmac_f32_e32 v2, v3, v1
	s_and_saveexec_b64 s[0:1], vcc
	s_xor_b64 s[0:1], exec, s[0:1]
	s_cbranch_execz .LBB0_393
	v_mul_f32_e32 v1, 0xbfb8aa3b, v2
	v_exp_f32_e32 v1, v1
	v_cmp_gt_u32_e32 vcc, s6, v0
	v_add_f32_e32 v1, 1.0, v1
	v_rcp_f32_e32 v1, v1
	s_nop 0
	v_cndmask_b32_e32 v1, v1, v2, vcc
